# w_o / mlp2 residual epilogue: the four row loads of each read-add-store round issued together, one wait per iteration (4 loops); on top of v113
# speedup vs baseline: 1.0034x; 1.0034x over previous
.LBB0_1508:
	s_waitcnt lgkmcnt(0)
	ds_read_b128 v[64:67], v77
	s_mov_b64 s[20:21], -1
	s_and_b64 vcc, exec, s[86:87]
	v_lshl_add_u64 v[74:75], v[68:69], 0, s[18:19]
	s_cbranch_vccz .LBB0_1510
	v_add_co_u32_e32 v84, vcc, 0x1000, v74
	s_nop 1
	v_addc_co_u32_e32 v85, vcc, 0, v75, vcc
	global_load_dwordx4 v[88:91], v[84:85], off
	v_add_co_u32_e32 v84, vcc, 0x2000, v74
	s_nop 1
	v_addc_co_u32_e32 v85, vcc, 0, v75, vcc
	global_load_dwordx4 v[92:95], v[84:85], off
	v_add_co_u32_e32 v84, vcc, 0x3000, v74
	s_nop 1
	v_addc_co_u32_e32 v85, vcc, 0, v75, vcc
	global_load_dwordx4 v[96:99], v[84:85], off
	global_load_dwordx4 v[78:81], v[74:75], off
	s_mov_b64 s[20:21], 0
	s_waitcnt vmcnt(0) lgkmcnt(0)
	v_pk_add_f32 v[80:81], v[66:67], v[80:81]
	v_pk_add_f32 v[78:79], v[64:65], v[78:79]
	global_store_dwordx4 v[74:75], v[78:81], off

.LBB0_1512:
	s_waitcnt lgkmcnt(0)
	ds_read_b128 v[64:67], v77 offset:1040
	v_cndmask_b32_e64 v78, 0, 1, s[86:87]
	v_cmp_ne_u32_e64 s[48:49], 1, v78
	s_andn2_b64 vcc, exec, s[86:87]
	s_mov_b64 s[20:21], -1
	s_cbranch_vccnz .LBB0_1518
	v_add_co_u32_e32 v82, vcc, 0x1000, v74
	s_nop 1
	v_addc_co_u32_e32 v83, vcc, 0, v75, vcc
	s_waitcnt lgkmcnt(0)
	v_pk_add_f32 v[80:81], v[66:67], v[90:91]
	v_pk_add_f32 v[78:79], v[64:65], v[88:89]
	global_store_dwordx4 v[82:83], v[78:81], off
	s_cbranch_execz .LBB0_1519

.LBB0_1515:
	v_add_co_u32_e32 v82, vcc, 0x2000, v74
	s_nop 1
	v_addc_co_u32_e32 v83, vcc, 0, v75, vcc
	s_waitcnt lgkmcnt(0)
	v_pk_add_f32 v[80:81], v[66:67], v[94:95]
	v_pk_add_f32 v[78:79], v[64:65], v[92:93]
	global_store_dwordx4 v[82:83], v[78:81], off
	s_cbranch_execz .LBB0_1521

.LBB0_1517:
	v_add_co_u32_e32 v74, vcc, 0x3000, v74
	s_nop 1
	v_addc_co_u32_e32 v75, vcc, 0, v75, vcc
	s_waitcnt lgkmcnt(0)
	v_pk_add_f32 v[80:81], v[66:67], v[98:99]
	v_pk_add_f32 v[78:79], v[64:65], v[96:97]
	global_store_dwordx4 v[74:75], v[78:81], off
	s_cbranch_execnz .LBB0_1507
	s_branch .LBB0_1523

.LBB0_1526:
	s_waitcnt lgkmcnt(0)
	ds_read_b128 v[0:3], v76
	s_mov_b64 s[16:17], -1
	s_and_b64 vcc, exec, s[86:87]
	v_lshl_add_u64 v[6:7], v[68:69], 0, s[14:15]
	s_cbranch_vccz .LBB0_1534
	v_add_co_u32_e32 v84, vcc, 0x81000, v6
	s_nop 1
	v_addc_co_u32_e32 v85, vcc, 0, v7, vcc
	global_load_dwordx4 v[88:91], v[84:85], off
	v_add_co_u32_e32 v84, vcc, 0x82000, v6
	s_nop 1
	v_addc_co_u32_e32 v85, vcc, 0, v7, vcc
	global_load_dwordx4 v[92:95], v[84:85], off
	v_add_co_u32_e32 v84, vcc, 0x83000, v6
	s_nop 1
	v_addc_co_u32_e32 v85, vcc, 0, v7, vcc
	global_load_dwordx4 v[96:99], v[84:85], off
	v_add_co_u32_e32 v12, vcc, 0x80000, v6
	s_nop 1
	v_addc_co_u32_e32 v13, vcc, 0, v7, vcc
	global_load_dwordx4 v[8:11], v[12:13], off
	s_waitcnt vmcnt(0) lgkmcnt(0)
	v_pk_add_f32 v[10:11], v[2:3], v[10:11]
	v_pk_add_f32 v[8:9], v[0:1], v[8:9]
	global_store_dwordx4 v[12:13], v[8:11], off
	s_cbranch_execz .LBB0_1535

.LBB0_1529:
	v_add_co_u32_e32 v12, vcc, 0x81000, v6
	s_nop 1
	v_addc_co_u32_e32 v13, vcc, 0, v7, vcc
	s_waitcnt lgkmcnt(0)
	v_pk_add_f32 v[10:11], v[2:3], v[90:91]
	v_pk_add_f32 v[8:9], v[0:1], v[88:89]
	global_store_dwordx4 v[12:13], v[8:11], off
	s_cbranch_execz .LBB0_1537

.LBB0_1531:
	v_add_co_u32_e32 v12, vcc, 0x82000, v6
	s_nop 1
	v_addc_co_u32_e32 v13, vcc, 0, v7, vcc
	s_waitcnt lgkmcnt(0)
	v_pk_add_f32 v[10:11], v[2:3], v[94:95]
	v_pk_add_f32 v[8:9], v[0:1], v[92:93]
	global_store_dwordx4 v[12:13], v[8:11], off
	s_cbranch_execz .LBB0_1539

.LBB0_1533:
	v_add_co_u32_e32 v10, vcc, 0x83000, v6
	s_nop 1
	v_addc_co_u32_e32 v11, vcc, 0, v7, vcc
	s_waitcnt lgkmcnt(0)
	v_pk_add_f32 v[8:9], v[2:3], v[98:99]
	v_pk_add_f32 v[6:7], v[0:1], v[96:97]
	global_store_dwordx4 v[10:11], v[6:9], off
	s_cbranch_execnz .LBB0_1525
	s_branch .LBB0_1541

.LBB0_1870:
	s_waitcnt lgkmcnt(0)
	ds_read_b128 v[64:67], v77 offset:1040
	v_cndmask_b32_e64 v78, 0, 1, s[86:87]
	v_cmp_ne_u32_e64 s[46:47], 1, v78
	s_andn2_b64 vcc, exec, s[86:87]
	s_mov_b64 s[20:21], -1
	s_cbranch_vccnz .LBB0_1876
	v_add_co_u32_e32 v82, vcc, 0x1000, v74
	s_nop 1
	v_addc_co_u32_e32 v83, vcc, 0, v75, vcc
	s_waitcnt lgkmcnt(0)
	v_pk_add_f32 v[80:81], v[66:67], v[90:91]
	v_pk_add_f32 v[78:79], v[64:65], v[88:89]
	global_store_dwordx4 v[82:83], v[78:81], off
	s_cbranch_execz .LBB0_1877
